# team barrier: L1 invalidate and first poll issued right behind the arrive atomic instead of serially after its return (12 seams)
# speedup vs baseline: 1.0098x; 1.0098x over previous
; __device__ __forceinline__ unsigned xb_ld(unsigned* p)              { return __hip_atomic_load(p, __ATOMIC_RELAXED, __HIP_MEMORY_SCOPE_AGENT); }
; __device__ __forceinline__ unsigned xb_add(unsigned* p, unsigned v) { return __hip_atomic_fetch_add(p, v, __ATOMIC_RELAXED, __HIP_MEMORY_SCOPE_AGENT); }
; #define XB_SPIN(cond, bar) do { unsigned _sp = 0; while (cond) { __builtin_amdgcn_s_sleep(1); \
;     if ((++_sp & 255u) == 0u) { if (xb_ld(&(bar)[XB_TMO])) break; if (_sp > XB_SPIN_CAP) { atomicAdd(&(bar)[XB_TMO], 1u); break; } } } } while (0)
; __device__ __forceinline__ void team_barrier(const Team& T) {
;     asm volatile("s_waitcnt vmcnt(0)" ::: "memory");
;     __syncthreads();
;     if (threadIdx.x == 0) {
;         __builtin_amdgcn_s_waitcnt(0);
;         if (!T.same) { __builtin_amdgcn_fence(__ATOMIC_RELEASE, "agent"); asm volatile("s_waitcnt vmcnt(0)" ::: "memory"); }
;         const unsigned old = xb_add(T.cnt, 1u), target = (old / 4u + 1u) * 4u;
;         XB_SPIN(xb_ld(T.cnt) < target, T.tmo);
;         __builtin_amdgcn_fence(__ATOMIC_ACQUIRE, "agent");
;         asm volatile("s_waitcnt vmcnt(0)" ::: "memory");
;     }
;     __syncthreads();
; }
.LBB0_472:
	v_readlane_b32 s0, v254, 39
	v_mov_b32_e32 v0, 0
	v_mov_b32_e32 v1, 1
	v_readlane_b32 s1, v254, 40
	s_nop 4
	global_atomic_add v1, v0, v1, s[0:1] sc0
	buffer_inv sc1
	global_load_dword v2, v0, s[0:1] sc1
	s_waitcnt vmcnt(0)
	v_and_b32_e32 v1, -4, v1
	v_add_u32_e32 v1, 4, v1
	v_cmp_lt_u32_e32 vcc, v2, v1
	s_and_saveexec_b64 s[0:1], vcc
	s_cbranch_execz .LBB0_484
	s_mov_b32 s4, 1
	s_mov_b64 s[6:7], 0
	s_branch .LBB0_475

; __device__ __forceinline__ unsigned xb_ld(unsigned* p)              { return __hip_atomic_load(p, __ATOMIC_RELAXED, __HIP_MEMORY_SCOPE_AGENT); }
; #define XB_SPIN(cond, bar) do { unsigned _sp = 0; while (cond) { __builtin_amdgcn_s_sleep(1); \
;     if ((++_sp & 255u) == 0u) { if (xb_ld(&(bar)[XB_TMO])) break; if (_sp > XB_SPIN_CAP) { atomicAdd(&(bar)[XB_TMO], 1u); break; } } } } while (0)
; __device__ __forceinline__ void team_barrier(const Team& T) {
;     ...
;         XB_SPIN(xb_ld(T.cnt) < target, T.tmo);
;         __builtin_amdgcn_fence(__ATOMIC_ACQUIRE, "agent");
;         asm volatile("s_waitcnt vmcnt(0)" ::: "memory");
;     }
.LBB0_484:
	s_or_b64 exec, exec, s[0:1]
	s_waitcnt vmcnt(0)
	s_waitcnt vmcnt(0)

; __device__ __forceinline__ unsigned xb_ld(unsigned* p)              { return __hip_atomic_load(p, __ATOMIC_RELAXED, __HIP_MEMORY_SCOPE_AGENT); }
; __device__ __forceinline__ unsigned xb_add(unsigned* p, unsigned v) { return __hip_atomic_fetch_add(p, v, __ATOMIC_RELAXED, __HIP_MEMORY_SCOPE_AGENT); }
; #define XB_SPIN(cond, bar) do { unsigned _sp = 0; while (cond) { __builtin_amdgcn_s_sleep(1); \
;     if ((++_sp & 255u) == 0u) { if (xb_ld(&(bar)[XB_TMO])) break; if (_sp > XB_SPIN_CAP) { atomicAdd(&(bar)[XB_TMO], 1u); break; } } } } while (0)
; __device__ __forceinline__ void team_barrier(const Team& T) {
;     asm volatile("s_waitcnt vmcnt(0)" ::: "memory");
;     __syncthreads();
;     if (threadIdx.x == 0) {
;         __builtin_amdgcn_s_waitcnt(0);
;         if (!T.same) { __builtin_amdgcn_fence(__ATOMIC_RELEASE, "agent"); asm volatile("s_waitcnt vmcnt(0)" ::: "memory"); }
;         const unsigned old = xb_add(T.cnt, 1u), target = (old / 4u + 1u) * 4u;
;         XB_SPIN(xb_ld(T.cnt) < target, T.tmo);
;         __builtin_amdgcn_fence(__ATOMIC_ACQUIRE, "agent");
;         asm volatile("s_waitcnt vmcnt(0)" ::: "memory");
.LBB0_2342:
	v_readlane_b32 s0, v254, 39
	v_mov_b32_e32 v0, 0
	v_mov_b32_e32 v1, 1
	v_readlane_b32 s1, v254, 40
	s_nop 4
	global_atomic_add v1, v0, v1, s[0:1] sc0
	buffer_inv sc1
	global_load_dword v2, v0, s[0:1] sc1
	s_waitcnt vmcnt(0)
	v_and_b32_e32 v1, -4, v1
	v_add_u32_e32 v1, 4, v1
	v_cmp_lt_u32_e32 vcc, v2, v1
	s_and_saveexec_b64 s[0:1], vcc
	s_cbranch_execz .LBB0_2354
	s_mov_b32 s3, 1
	s_mov_b64 s[6:7], 0
	s_branch .LBB0_2345
